# MLA tile body: DMA issue block for the tile two steps ahead moved from the body head to just after the QK MFMAs are issued
# speedup vs baseline: 1.0652x; 1.0036x over previous
; template <int DQK, int DV, bool FOX> ...
;     ...
;     for (int t = 0; t < NT; ++t) {
;         if (t + 2 < NT) ATT_DMA(t + 2, bn2);
;         if (t < ntw) {
.LBB0_706:
	s_add_i32 s1, s25, 2
	s_cmp_ge_u32 s1, s24
	s_cselect_b64 s[22:23], -1, 0
	s_cmp_gt_u32 s25, s7
	s_cbranch_scc0 .LBB0_723
	s_and_b64 vcc, exec, s[22:23]
	s_cbranch_vccnz .LBB0_722
	s_and_saveexec_b64 s[2:3], s[14:15]
	s_xor_b64 s[2:3], exec, s[2:3]
	v_lshl_add_u64 v[66:67], s[90:91], 0, v[204:205]
	v_lshl_add_u64 v[66:67], v[66:67], 0, v[150:151]
	s_andn2_saveexec_b64 s[2:3], s[2:3]
	v_lshl_add_u64 v[66:67], s[90:91], 0, v[190:191]
	v_lshl_add_u64 v[66:67], v[66:67], 0, s[40:41]
	s_or_b64 exec, exec, s[2:3]
	s_mul_i32 s1, s11, 0xa100
	s_add_i32 s1, s1, 0
	s_add_i32 s2, s1, s5
	s_mov_b32 s3, m0
	s_mov_b32 m0, s2
	s_nop 0
	global_load_lds_dwordx4 v[66:67], off
	s_mov_b32 m0, s3
	s_and_saveexec_b64 s[2:3], s[16:17]
	s_xor_b64 s[2:3], exec, s[2:3]
	v_lshl_add_u64 v[66:67], s[90:91], 0, v[206:207]
	v_mov_b32_e32 v193, v151
	v_lshl_add_u64 v[66:67], v[66:67], 0, v[192:193]
	s_andn2_saveexec_b64 s[2:3], s[2:3]
	v_lshl_add_u64 v[66:67], s[90:91], 0, v[198:199]
	v_lshl_add_u64 v[66:67], v[66:67], 0, s[40:41]
	s_or_b64 exec, exec, s[2:3]
	s_add_i32 s2, s1, s8
	s_mov_b32 s3, m0
	s_mov_b32 m0, s2
	s_nop 0
	global_load_lds_dwordx4 v[66:67], off
	s_mov_b32 m0, s3
	s_and_saveexec_b64 s[2:3], s[18:19]
	s_xor_b64 s[2:3], exec, s[2:3]
	v_lshl_add_u64 v[66:67], s[90:91], 0, v[208:209]
	v_mov_b32_e32 v195, v151
	v_lshl_add_u64 v[66:67], v[66:67], 0, v[194:195]
	s_andn2_saveexec_b64 s[2:3], s[2:3]
	v_lshl_add_u64 v[66:67], s[90:91], 0, v[200:201]
	v_lshl_add_u64 v[66:67], v[66:67], 0, s[40:41]
	s_or_b64 exec, exec, s[2:3]
	s_add_i32 s2, s1, s21
	s_mov_b32 s3, m0
	s_mov_b32 m0, s2
	s_nop 0
	global_load_lds_dwordx4 v[66:67], off
	s_mov_b32 m0, s3
	s_add_i32 s2, s1, 0x6000
	v_lshl_add_u64 v[66:67], s[90:91], 0, v[202:203]
	s_add_i32 s1, s2, s5
	v_lshl_add_u64 v[68:69], v[66:67], 0, s[84:85]
	s_mov_b32 s3, m0
	s_mov_b32 m0, s1
	s_nop 0
	global_load_lds_dwordx4 v[68:69], off
	s_mov_b32 m0, s3
	s_mov_b32 s1, s85
	v_lshl_add_u64 v[66:67], v[66:67], 0, s[0:1]
	s_add_i32 s1, s2, s8
	s_mov_b32 s2, m0
	s_mov_b32 m0, s1
	s_nop 0
	global_load_lds_dwordx4 v[66:67], off
	s_mov_b32 m0, s2
	s_cmp_gt_u32 s25, s7
	s_cbranch_scc0 .LBB0_723

; #define LAS __attribute__((address_space(3)))
; template <int DQK, int DV, bool FOX> ...
;     ...
;                 for (int g0 = 0; g0 < ND0; g0 += GB) { bf16x8 ka[GB], kb[GB];
; #pragma unroll
;                     for (int j = 0; j < GB; ++j) { const int c = 2 * (g0 + j) + h; const int co = ((c & ~7) | ((c ^ ksw) & 7)) * 16;
;                         ka[j] = *(const LAS bf16x8*)(b + kread0 + co); kb[j] = *(const LAS bf16x8*)(b + kread0 + 32 * KROW + co); }
;                     __builtin_amdgcn_sched_barrier(0);
; #pragma unroll
;                     for (int j = 0; j < GB; ++j) { p0 = __builtin_amdgcn_mfma_f32_32x32x16_bf16(ka[j], qf[g0 + j], p0, 0, 0, 0);
;                                                    p1 = __builtin_amdgcn_mfma_f32_32x32x16_bf16(kb[j], qf[g0 + j], p1, 0, 0, 0); }
;                     __builtin_amdgcn_sched_barrier(0); } }
.LBB0_723:
	s_mul_i32 s1, s6, 0xa100
	s_add_i32 s1, s1, 0
	v_mul_u32_u24_e32 v66, 0x180, v146
	v_add_u32_e32 v193, s1, v66
	v_add_u32_e32 v195, v193, v197
	v_add_u32_e32 v210, v193, v211
	v_add_u32_e32 v254, v193, v212
	v_add_u32_e32 v193, v193, v213
	ds_read_b128 v[66:69], v195
	ds_read_b128 v[70:73], v195 offset:12288
	ds_read_b128 v[234:237], v210
	ds_read_b128 v[238:241], v210 offset:12288
	ds_read_b128 v[242:245], v254
	ds_read_b128 v[246:249], v254 offset:12288
	s_waitcnt lgkmcnt(5)
	v_mfma_f32_32x32x16_bf16 v[82:97], v[66:69], v[98:101], 0
	ds_read_b128 v[250:253], v193
	s_waitcnt lgkmcnt(5)
	v_mfma_f32_32x32x16_bf16 v[66:81], v[70:73], v[98:101], 0
	ds_read_b128 v[214:217], v193 offset:12288
	s_waitcnt lgkmcnt(5)
	v_mfma_f32_32x32x16_bf16 v[82:97], v[234:237], v[102:105], v[82:97]
	ds_read_b128 v[234:237], v195 offset:128
	s_waitcnt lgkmcnt(5)
	v_mfma_f32_32x32x16_bf16 v[66:81], v[238:241], v[102:105], v[66:81]
	ds_read_b128 v[238:241], v195 offset:12416
	s_waitcnt lgkmcnt(5)
	v_mfma_f32_32x32x16_bf16 v[82:97], v[242:245], v[106:109], v[82:97]
	ds_read_b128 v[242:245], v210 offset:128
	s_waitcnt lgkmcnt(5)
	v_mfma_f32_32x32x16_bf16 v[66:81], v[246:249], v[106:109], v[66:81]
	ds_read_b128 v[246:249], v210 offset:12416
	s_waitcnt lgkmcnt(5)
	v_mfma_f32_32x32x16_bf16 v[82:97], v[250:253], v[110:113], v[82:97]
	ds_read_b128 v[250:253], v254 offset:128
	s_waitcnt lgkmcnt(5)
	v_mfma_f32_32x32x16_bf16 v[66:81], v[214:217], v[110:113], v[66:81]
	ds_read_b128 v[214:217], v254 offset:12416
	s_waitcnt lgkmcnt(5)
	v_mfma_f32_32x32x16_bf16 v[82:97], v[234:237], v[114:117], v[82:97]
	ds_read_b128 v[234:237], v193 offset:128
	s_waitcnt lgkmcnt(5)
	v_mfma_f32_32x32x16_bf16 v[66:81], v[238:241], v[114:117], v[66:81]
	ds_read_b128 v[238:241], v193 offset:12416
	s_waitcnt lgkmcnt(5)
	v_mfma_f32_32x32x16_bf16 v[82:97], v[242:245], v[118:121], v[82:97]
	ds_read_b128 v[242:245], v195 offset:256
	s_waitcnt lgkmcnt(5)
	v_mfma_f32_32x32x16_bf16 v[66:81], v[246:249], v[118:121], v[66:81]
	ds_read_b128 v[246:249], v195 offset:12544
	s_waitcnt lgkmcnt(5)
	v_mfma_f32_32x32x16_bf16 v[82:97], v[250:253], v[122:125], v[82:97]
	ds_read_b128 v[250:253], v210 offset:256
	s_waitcnt lgkmcnt(5)
	v_mfma_f32_32x32x16_bf16 v[66:81], v[214:217], v[122:125], v[66:81]
	ds_read_b128 v[214:217], v210 offset:12544
	s_waitcnt lgkmcnt(5)
	v_mfma_f32_32x32x16_bf16 v[82:97], v[234:237], v[126:129], v[82:97]
	ds_read_b128 v[234:237], v254 offset:256
	s_waitcnt lgkmcnt(5)
	v_mfma_f32_32x32x16_bf16 v[66:81], v[238:241], v[126:129], v[66:81]
	ds_read_b128 v[238:241], v254 offset:12544
	s_waitcnt lgkmcnt(5)
	v_mfma_f32_32x32x16_bf16 v[82:97], v[242:245], v[130:133], v[82:97]
	ds_read_b128 v[242:245], v193 offset:256
	s_waitcnt lgkmcnt(5)
	v_mfma_f32_32x32x16_bf16 v[66:81], v[246:249], v[130:133], v[66:81]
	ds_read_b128 v[246:249], v193 offset:12544
	s_waitcnt lgkmcnt(5)
	v_mfma_f32_32x32x16_bf16 v[82:97], v[250:253], v[134:137], v[82:97]
	s_waitcnt lgkmcnt(4)
	v_mfma_f32_32x32x16_bf16 v[66:81], v[214:217], v[134:137], v[66:81]
	s_waitcnt lgkmcnt(3)
	v_mfma_f32_32x32x16_bf16 v[82:97], v[234:237], v[138:141], v[82:97]
	s_waitcnt lgkmcnt(2)
	v_mfma_f32_32x32x16_bf16 v[66:81], v[238:241], v[138:141], v[66:81]
	s_waitcnt lgkmcnt(1)
	v_mfma_f32_32x32x16_bf16 v[82:97], v[242:245], v[142:145], v[82:97]
	s_waitcnt lgkmcnt(0)
	v_mfma_f32_32x32x16_bf16 v[66:81], v[246:249], v[142:145], v[66:81]
	s_and_b64 vcc, exec, s[22:23]
	s_cbranch_vccnz .Lmla_nodma
	s_and_saveexec_b64 s[2:3], s[14:15]
	s_xor_b64 s[2:3], exec, s[2:3]
	v_lshl_add_u64 v[250:251], s[90:91], 0, v[204:205]
	v_lshl_add_u64 v[250:251], v[250:251], 0, v[150:151]
	s_andn2_saveexec_b64 s[2:3], s[2:3]
	v_lshl_add_u64 v[250:251], s[90:91], 0, v[190:191]
	v_lshl_add_u64 v[250:251], v[250:251], 0, s[40:41]
	s_or_b64 exec, exec, s[2:3]
	s_mul_i32 s99, s11, 0xa100
	s_add_i32 s99, s99, 0
	s_add_i32 s2, s99, s5
	s_mov_b32 s3, m0
	s_mov_b32 m0, s2
	s_nop 0
	global_load_lds_dwordx4 v[250:251], off
	s_mov_b32 m0, s3
	s_and_saveexec_b64 s[2:3], s[16:17]
	s_xor_b64 s[2:3], exec, s[2:3]
	v_lshl_add_u64 v[250:251], s[90:91], 0, v[206:207]
	v_mov_b32_e32 v193, v151
	v_lshl_add_u64 v[250:251], v[250:251], 0, v[192:193]
	s_andn2_saveexec_b64 s[2:3], s[2:3]
	v_lshl_add_u64 v[250:251], s[90:91], 0, v[198:199]
	v_lshl_add_u64 v[250:251], v[250:251], 0, s[40:41]
	s_or_b64 exec, exec, s[2:3]
	s_add_i32 s2, s99, s8
	s_mov_b32 s3, m0
	s_mov_b32 m0, s2
	s_nop 0
	global_load_lds_dwordx4 v[250:251], off
	s_mov_b32 m0, s3
	s_and_saveexec_b64 s[2:3], s[18:19]
	s_xor_b64 s[2:3], exec, s[2:3]
	v_lshl_add_u64 v[250:251], s[90:91], 0, v[208:209]
	v_mov_b32_e32 v195, v151
	v_lshl_add_u64 v[250:251], v[250:251], 0, v[194:195]
	s_andn2_saveexec_b64 s[2:3], s[2:3]
	v_lshl_add_u64 v[250:251], s[90:91], 0, v[200:201]
	v_lshl_add_u64 v[250:251], v[250:251], 0, s[40:41]
	s_or_b64 exec, exec, s[2:3]
	s_add_i32 s2, s99, s21
	s_mov_b32 s3, m0
	s_mov_b32 m0, s2
	s_nop 0
	global_load_lds_dwordx4 v[250:251], off
	s_mov_b32 m0, s3
	s_add_i32 s2, s99, 0x6000
	v_lshl_add_u64 v[250:251], s[90:91], 0, v[202:203]
	s_add_i32 s99, s2, s5
	v_lshl_add_u64 v[252:253], v[250:251], 0, s[84:85]
	s_mov_b32 s3, m0
	s_mov_b32 m0, s99
	s_nop 0
	global_load_lds_dwordx4 v[252:253], off
	s_mov_b32 m0, s3
	s_mov_b32 s100, s0
	s_mov_b32 s101, s85
	v_lshl_add_u64 v[250:251], v[250:251], 0, s[100:101]
	s_add_i32 s99, s2, s8
	s_mov_b32 s2, m0
	s_mov_b32 m0, s99
	s_nop 0
	global_load_lds_dwordx4 v[250:251], off
	s_mov_b32 m0, s2
; #define LAS __attribute__((address_space(3)))
; template <int DQK, int DV, bool FOX> ...
;     ...
;             float rm = fmaxf(fmaxf(p0[0], p1[0]), p0[1]);
; #pragma unroll
;             for (int i = 1; i < 15; ++i) rm = fmaxf(fmaxf(rm, p1[i]), p0[i + 1]);
;             rm = fmaxf(rm, p1[15]);
;             { const auto rr_ = __builtin_amdgcn_permlane32_swap(__float_as_uint(rm), __float_as_uint(rm), false, false);
;               rm = fmaxf(__uint_as_float(rr_[0]), __uint_as_float(rr_[1])); }
;             const bool grow = rm > mloc + THR;
;             if (__any(grow)) {
;                 const float mnew = grow ? rm : mloc; const float al = __builtin_amdgcn_exp2f(mloc - mnew);
;                 lsum *= al; mref = grow ? (mnew + cqt) : mref; mloc = mnew;
;                 if (h == 0) wsf[r] = al;
;                 asm volatile("s_waitcnt lgkmcnt(0)" ::: "memory");
; #pragma unroll
;                 for (int g = 0; g < 4; ++g) { const f32x4 a4 = *(const LAS f32x4*)(wsf + 8 * g + 4 * h);
; #pragma unroll
;                     for (int cb = 0; cb < NCB; ++cb)
; #pragma unroll
;                         for (int e = 0; e < 4; ++e) o[cb][4 * g + e] *= a4[e]; }
;             }
.Lmla_nodma:
	s_nop 11
	v_max_f32_e32 v193, v66, v66
	v_max_f32_e32 v195, v82, v82
	v_max_f32_e32 v193, v195, v193
	v_max3_f32 v193, v193, v83, v67
	v_max3_f32 v193, v193, v84, v68
	v_max3_f32 v193, v193, v85, v69
	v_max3_f32 v193, v193, v86, v70
	v_max3_f32 v193, v193, v87, v71
	v_max3_f32 v193, v193, v88, v72
	v_max3_f32 v193, v193, v89, v73
	v_max3_f32 v193, v193, v90, v74
	v_max3_f32 v193, v193, v91, v75
	v_max3_f32 v193, v193, v92, v76
	v_max3_f32 v193, v193, v93, v77
	v_max3_f32 v193, v193, v94, v78
	v_max3_f32 v193, v193, v95, v79
	v_max3_f32 v193, v193, v96, v80
	v_max3_f32 v193, v193, v97, v81
	v_mov_b32_e32 v195, v193
	s_nop 1
	v_permlane32_swap_b32_e32 v193, v195
	v_max_f32_e32 v195, v195, v195
	v_max_f32_e32 v193, v193, v193
	v_max_f32_e32 v193, v193, v195
	v_add_f32_e32 v195, 0x40c00000, v233
	v_cmp_gt_f32_e32 vcc, v193, v195
	s_cbranch_vccz .LBB0_727
	s_nop 0
	v_cndmask_b32_e32 v210, v233, v193, vcc
	v_sub_f32_e32 v195, v233, v210
	v_exp_f32_e32 v195, v195
	s_and_saveexec_b64 s[2:3], s[12:13]
	ds_write_b32 v231, v195
	s_or_b64 exec, exec, s[2:3]
	s_waitcnt lgkmcnt(0)
	ds_read_b128 v[214:217], v230 offset:64
	ds_read_b128 v[234:237], v230 offset:96
	ds_read_b128 v[238:241], v230
	ds_read_b128 v[242:245], v230 offset:32
	v_add_f32_e32 v193, 0, v193
	v_mul_f32_e32 v232, v232, v195
	v_cndmask_b32_e32 v233, v233, v193, vcc
	s_waitcnt lgkmcnt(2)
	v_pk_mul_f32 v[64:65], v[64:65], v[236:237]
	v_pk_mul_f32 v[60:61], v[60:61], v[216:217]
	s_waitcnt lgkmcnt(0)
	v_pk_mul_f32 v[56:57], v[56:57], v[244:245]
	v_pk_mul_f32 v[52:53], v[52:53], v[240:241]
	v_pk_mul_f32 v[62:63], v[62:63], v[234:235]
	v_pk_mul_f32 v[58:59], v[58:59], v[214:215]
	v_pk_mul_f32 v[54:55], v[54:55], v[242:243]
	v_pk_mul_f32 v[50:51], v[50:51], v[238:239]
	v_pk_mul_f32 v[48:49], v[48:49], v[236:237]
	v_pk_mul_f32 v[44:45], v[44:45], v[216:217]
	v_pk_mul_f32 v[40:41], v[40:41], v[244:245]
	v_pk_mul_f32 v[36:37], v[36:37], v[240:241]
	v_pk_mul_f32 v[46:47], v[46:47], v[234:235]
	v_pk_mul_f32 v[42:43], v[42:43], v[214:215]
	v_pk_mul_f32 v[38:39], v[38:39], v[242:243]
	v_pk_mul_f32 v[34:35], v[34:35], v[238:239]
	v_pk_mul_f32 v[32:33], v[32:33], v[236:237]
	v_pk_mul_f32 v[28:29], v[28:29], v[216:217]
	v_pk_mul_f32 v[24:25], v[24:25], v[244:245]
	v_pk_mul_f32 v[20:21], v[20:21], v[240:241]
	v_pk_mul_f32 v[30:31], v[30:31], v[234:235]
	v_pk_mul_f32 v[26:27], v[26:27], v[214:215]
	v_pk_mul_f32 v[22:23], v[22:23], v[242:243]
	v_pk_mul_f32 v[18:19], v[18:19], v[238:239]
	v_pk_mul_f32 v[16:17], v[16:17], v[236:237]
	v_pk_mul_f32 v[12:13], v[12:13], v[216:217]
	v_pk_mul_f32 v[8:9], v[8:9], v[244:245]
	v_pk_mul_f32 v[4:5], v[4:5], v[240:241]
	v_pk_mul_f32 v[14:15], v[14:15], v[234:235]
	v_pk_mul_f32 v[10:11], v[10:11], v[214:215]
	v_pk_mul_f32 v[6:7], v[6:7], v[242:243]
	v_pk_mul_f32 v[2:3], v[2:3], v[238:239]
	s_branch .LBB0_728
